# grid barrier: waiting work-groups poll the top-level generation word directly (one fewer propagation hop)
# baseline (speedup 1.0000x reference)
.LBB0_89:
	s_or_b64 exec, exec, s[2:3]
	v_cvt_f32_u32_e32 v5, v3
	s_waitcnt vmcnt(0)
	v_readfirstlane_b32 s2, v4
	v_sub_u32_e32 v4, 0, v3
	v_rcp_iflag_f32_e32 v5, v5
	v_add_u32_e32 v6, s2, v1
	v_mul_f32_e32 v5, 0x4f7ffffe, v5
	v_cvt_u32_f32_e32 v5, v5
	v_mul_lo_u32 v1, v4, v5
	v_mul_hi_u32 v1, v5, v1
	v_add_u32_e32 v1, v5, v1
	v_mul_hi_u32 v1, v6, v1
	v_mul_lo_u32 v4, v1, v3
	v_sub_u32_e32 v4, v6, v4
	v_add_u32_e32 v5, 1, v1
	v_cmp_ge_u32_e32 vcc, v4, v3
	s_nop 1
	v_cndmask_b32_e32 v1, v1, v5, vcc
	v_sub_u32_e32 v5, v4, v3
	v_cndmask_b32_e32 v4, v4, v5, vcc
	v_add_u32_e32 v5, 1, v1
	v_cmp_ge_u32_e32 vcc, v4, v3
	v_add_u32_e32 v4, 1, v6
	s_nop 0
	v_cndmask_b32_e32 v1, v1, v5, vcc
	v_mul_lo_u32 v5, v3, v1
	v_add_u32_e32 v3, v5, v3
	v_cmp_ne_u32_e32 vcc, v4, v3
	s_and_saveexec_b64 s[2:3], vcc
	s_xor_b64 s[2:3], exec, s[2:3]
	s_cbranch_execz .LBB0_103
	v_readlane_b32 s4, v254, 15
	v_readlane_b32 s5, v254, 16
	s_waitcnt lgkmcnt(0)
	s_nop 3
	global_load_dword v2, v0, s[4:5] sc1
	s_waitcnt vmcnt(0)
	v_cmp_eq_u32_e32 vcc, v2, v1
	s_and_saveexec_b64 s[4:5], vcc
	s_cbranch_execz .LBB0_102
	s_mov_b32 s16, 1
	s_mov_b64 s[6:7], 0
	s_branch .LBB0_93
